# full HGRN pass: Q/K decay products converted to bf16 pairwise (one v_cvt_pk per token, hi half stored with ds_write_b16_d16_hi)
# baseline (speedup 1.0000x reference)
; #define LAS __attribute__((address_space(3)))
; __device__ __forceinline__ unsigned cvt_pk_bf16(float lo, float hi) { unsigned r; asm volatile("v_cvt_pk_bf16_f32 %0, %1, %2" : "=v"(r) : "v"(lo), "v"(hi)); return r; }
; __device__ __forceinline__ float bf2f(unsigned short b) { return __uint_as_float(((unsigned)b) << 16); }
; template <bool FULL>
; __device__ __forceinline__ void hgrn_item(LAS unsigned char* lds, const bf16_t* P, bf16_t* AB, int L, int hd, const float* lbv, const float* anorm, const float* S0, const float* Dd, int ns, float* Sout, float* Dout) {
;     ...
;             float run = 0.f;
; #pragma unroll
;             for (int i = 0; i < 4; ++i) { float z = bf2f(zc[i]); z = fminf(fmaxf(z, -30.f), 30.f); const float e = __expf(-z), sg = __builtin_amdgcn_rcpf(1.f + e), sn = e * sg;
;                 const float f = lb + oml * sg; run += __builtin_amdgcn_logf(f) * 0.69314718056f; cs[i] = run; kk[i] = oml * sn; qv[i] = bf2f(qc[i]); }
;             qsum[tq * 128 + k] = run;
;         }
;         __syncthreads();
;         {
;             float pre = 0.f, tot = 0.f;
; #pragma unroll
;             for (int j = 0; j < 4; ++j) { const float v = qsum[j * 128 + k]; tot += v; pre += (j < tq) ? v : 0.f; }
;             btot += tot;
;             float kh[4];
; #pragma unroll
;             for (int i = 0; i < 4; ++i) { const float b = pre + cs[i]; const float qt = qv[i] * __expf(b), kt = kk[i] * __expf(fminf(-b, 80.f)); kh[i] = kk[i] * __expf(tot - b);
;                 Qt[(4 * tq + i) * 136 + k] = (bf16_t)(cvt_pk_bf16(qt, 0.f) & 0xffffu); Kt[(4 * tq + i) * 136 + k] = (bf16_t)(cvt_pk_bf16(kt, 0.f) & 0xffffu); }
;             u32x2 kp; kp.x = cvt_pk_bf16(kh[0], kh[1]); kp.y = cvt_pk_bf16(kh[2], kh[3]);
;             *(LAS u32x2*)(KhT + k * 20 + 4 * tq) = kp;
;             if (tq == 0) dvec[k] = __expf(tot);
.LBB0_333:
	s_or_b64 exec, exec, s[0:1]
	v_lshlrev_b32_e32 v51, 16, v41
	v_lshlrev_b32_e32 v41, 16, v44
	v_max_f32_e32 v41, v41, v41
	v_med3_f32 v41, v41, s29, v225
	v_mul_f32_e32 v41, 0xbfb8aa3b, v41
	v_exp_f32_e32 v41, v41
	v_lshlrev_b32_e32 v47, 16, v47
	v_max_f32_e32 v47, v47, v47
	v_lshlrev_b32_e32 v45, 16, v45
	v_add_f32_e32 v44, 1.0, v41
	v_rcp_f32_e32 v44, v44
	v_med3_f32 v47, v47, s29, v225
	v_max_f32_e32 v45, v45, v45
	v_mul_f32_e32 v47, 0xbfb8aa3b, v47
	v_mul_f32_e32 v41, v41, v44
	v_med3_f32 v45, v45, s29, v225
	v_mul_f32_e32 v52, v89, v41
	v_lshlrev_b32_e32 v41, 16, v42
	v_exp_f32_e32 v47, v47
	v_mul_f32_e32 v45, 0xbfb8aa3b, v45
	v_max_f32_e32 v41, v41, v41
	v_exp_f32_e32 v45, v45
	v_med3_f32 v41, v41, s29, v225
	v_mul_f32_e32 v41, 0xbfb8aa3b, v41
	v_exp_f32_e32 v41, v41
	v_add_f32_e32 v48, 1.0, v47
	v_rcp_f32_e32 v48, v48
	v_add_f32_e32 v49, 1.0, v45
	v_rcp_f32_e32 v49, v49
	v_add_f32_e32 v42, 1.0, v41
	v_rcp_f32_e32 v42, v42
	v_mul_f32_e32 v47, v47, v48
	v_fma_f32 v48, v89, v48, v103
	v_log_f32_e32 v48, v48
	v_mul_f32_e32 v45, v45, v49
	v_fma_f32 v49, v89, v49, v103
	v_log_f32_e32 v49, v49
	v_fma_f32 v44, v89, v44, v103
	v_log_f32_e32 v44, v44
	v_mul_f32_e32 v41, v41, v42
	v_fma_f32 v42, v89, v42, v103
	v_log_f32_e32 v42, v42
	v_add_f32_e32 v49, v49, v48
	v_mul_f32_e32 v54, v89, v41
	v_add_f32_e32 v41, v44, v49
	v_add_f32_e32 v56, v42, v41
	v_lshlrev_b32_e32 v53, 16, v43
	ds_write_b32 v92, v56 offset:19456
	s_waitcnt lgkmcnt(0)
	s_barrier
	ds_read2st64_b32 v[42:43], v93 offset0:76 offset1:78
	ds_read2st64_b32 v[128:129], v93 offset0:80 offset1:82
	v_lshlrev_b32_e32 v55, 16, v40
	v_mul_f32_e32 v50, v89, v45
	v_lshlrev_b32_e32 v46, 16, v46
	v_mul_f32_e32 v47, v89, v47
	s_waitcnt lgkmcnt(1)
	v_add_f32_e32 v40, 0, v42
	v_cndmask_b32_e64 v42, 0, v40, s[40:41]
	v_add_f32_e32 v40, v40, v43
	v_cndmask_b32_e64 v43, 0, v43, s[42:43]
	v_add_f32_e32 v44, v42, v43
	s_waitcnt lgkmcnt(0)
	v_mov_b32_e32 v42, v128
	v_mov_b32_e32 v43, v129
	v_add_f32_e32 v40, v40, v42
	v_cndmask_b32_e64 v42, 0, v42, s[44:45]
	v_add_f32_e32 v42, v44, v42
	v_cndmask_b32_e64 v44, 0, v43, s[46:47]
	v_add_f32_e32 v45, v42, v44
	v_add_f32_e32 v42, v48, v45
	v_exp_f32_e32 v44, v42
	s_nop 0
	v_mul_f32_e32 v46, v44, v46
	v_min_f32_e64 v44, -v42, s99
	v_exp_f32_e32 v44, v44
	s_nop 0
	v_mul_f32_e32 v48, v47, v44
	v_mov_b32_e32 v44, v43
	v_cvt_pk_bf16_f32 v43, v46, v48
	ds_write_b16 v96, v43
	ds_write_b16_d16_hi v96, v43 offset:4352
	v_add_f32_e32 v43, v49, v45
	v_pk_add_f32 v[40:41], v[40:41], v[44:45]
	v_exp_f32_e32 v44, v43
	v_min_f32_e64 v46, -v43, s99
	v_exp_f32_e32 v46, v46
	v_mul_f32_e32 v44, v44, v51
	v_mul_f32_e32 v46, v50, v46
	v_cvt_pk_bf16_f32 v44, v44, v46
	ds_write_b16 v96, v44 offset:272
	ds_write_b16_d16_hi v96, v44 offset:4624
	v_exp_f32_e32 v44, v41
	v_min_f32_e64 v46, -v41, s99
	v_exp_f32_e32 v46, v46
	v_mul_f32_e32 v44, v44, v53
	v_mul_f32_e32 v46, v52, v46
	v_cvt_pk_bf16_f32 v44, v44, v46
	ds_write_b16 v96, v44 offset:544
	ds_write_b16_d16_hi v96, v44 offset:4896
	v_add_f32_e32 v44, v56, v45
	v_sub_f32_e32 v42, v40, v42
	v_sub_f32_e32 v43, v40, v43
	v_sub_f32_e32 v41, v40, v41
	v_exp_f32_e32 v45, v44
	v_min_f32_e64 v46, -v44, s99
	v_sub_f32_e32 v44, v40, v44
	v_exp_f32_e32 v42, v42
	v_exp_f32_e32 v43, v43
	v_exp_f32_e32 v41, v41
	v_exp_f32_e32 v46, v46
	v_exp_f32_e32 v44, v44
	v_mul_f32_e32 v45, v45, v55
	v_mul_f32_e32 v42, v47, v42
	v_mul_f32_e32 v43, v50, v43
	v_mul_f32_e32 v41, v52, v41
	v_mul_f32_e32 v46, v54, v46
	v_mul_f32_e32 v44, v54, v44
	v_cvt_pk_bf16_f32 v45, v45, v46
	ds_write_b16 v96, v45 offset:816
	ds_write_b16_d16_hi v96, v45 offset:5168
	v_cvt_pk_bf16_f32 v42, v42, v43
	v_cvt_pk_bf16_f32 v43, v41, v44
	ds_write_b64 v98, v[42:43] offset:8704
	s_and_saveexec_b64 s[0:1], s[36:37]
	s_cbranch_execz .LBB0_335
	v_exp_f32_e32 v40, v40
	ds_write_b32 v93, v40 offset:18944
